# k39 + in-epilogue quad-barrier polls and XCC-barrier loop polls also via scalar glc loads
# speedup vs baseline: 1.0007x; 1.0007x over previous
.LBB0_403:
	s_load_dword s100, s[42:43], 0x0 glc
	s_add_i32 s26, s26, 1
	s_mov_b64 s[58:59], -1
	s_waitcnt lgkmcnt(0)
	v_cmp_ne_u32_e32 vcc, s100, v0
	s_orn2_b64 s[50:51], vcc, exec
	s_branch .LBB0_400

.LBB0_420:
	s_load_dword s100, s[22:23], 0x0 glc
	s_add_i32 s26, s26, 1
	s_mov_b64 s[50:51], -1
	s_waitcnt lgkmcnt(0)
	v_cmp_ne_u32_e32 vcc, s100, v0
	s_orn2_b64 s[48:49], vcc, exec
	s_branch .LBB0_417

.LBB0_703:
	s_load_dword s100, s[50:51], 0x0 glc
	s_add_i32 s4, s4, 1
	s_mov_b64 s[68:69], -1
	s_waitcnt lgkmcnt(0)
	v_cmp_ne_u32_e32 vcc, s100, v0
	s_orn2_b64 s[66:67], vcc, exec
	s_branch .LBB0_700

.LBB0_720:
	s_load_dword s100, s[24:25], 0x0 glc
	s_add_i32 s4, s4, 1
	s_mov_b64 s[66:67], -1
	s_waitcnt lgkmcnt(0)
	v_cmp_ne_u32_e32 vcc, s100, v0
	s_orn2_b64 s[60:61], vcc, exec
	s_branch .LBB0_717

.LBB0_843:
	s_or_b64 exec, exec, s[42:43]
	s_waitcnt vmcnt(0)
	v_readfirstlane_b32 s4, v2
	s_nop 1
	v_add_u32_e32 v0, s4, v0
	v_and_b32_e32 v2, 3, v0
	v_cmp_ne_u32_e32 vcc, 3, v2
	s_and_saveexec_b64 s[40:41], vcc
	s_cbranch_execz .LBB0_858
	s_load_dword s100, s[24:25], 0x0 glc
	v_bitop3_b32 v0, v0, -4, v0 bitop3:0xc
	s_waitcnt lgkmcnt(0)
	v_add_u32_e32 v2, s100, v0
	v_cmp_gt_i32_e32 vcc, 0, v2
	s_and_b64 exec, exec, vcc
	s_cbranch_execz .LBB0_858
	s_add_u32 s22, s22, 0x4200
	s_addc_u32 s23, s23, 0
	s_mov_b32 s4, 1
	s_mov_b64 s[42:43], 0
	s_branch .LBB0_847

.LBB0_849:
	s_load_dword s100, s[24:25], 0x0 glc
	s_add_i32 s4, s4, 1
	s_mov_b64 s[58:59], -1
	s_waitcnt lgkmcnt(0)
	v_add_u32_e32 v2, s100, v0
	v_cmp_lt_i32_e32 vcc, -1, v2
	s_orn2_b64 s[50:51], vcc, exec
	s_branch .LBB0_846

.LBB0_891:
	s_or_b64 exec, exec, s[42:43]
	s_waitcnt vmcnt(0)
	v_readfirstlane_b32 s4, v2
	s_nop 1
	v_add_u32_e32 v0, s4, v0
	v_and_b32_e32 v2, 3, v0
	v_cmp_ne_u32_e32 vcc, 3, v2
	s_and_saveexec_b64 s[40:41], vcc
	s_cbranch_execz .LBB0_906
	s_load_dword s100, s[24:25], 0x0 glc
	v_bitop3_b32 v0, v0, -4, v0 bitop3:0xc
	s_waitcnt lgkmcnt(0)
	v_add_u32_e32 v2, s100, v0
	v_cmp_gt_i32_e32 vcc, 0, v2
	s_and_b64 exec, exec, vcc
	s_cbranch_execz .LBB0_906
	s_add_u32 s6, s6, 0x4200
	s_addc_u32 s7, s7, 0
	s_mov_b32 s4, 1
	s_mov_b64 s[42:43], 0
	s_branch .LBB0_895

.LBB0_897:
	s_load_dword s100, s[24:25], 0x0 glc
	s_add_i32 s4, s4, 1
	s_mov_b64 s[50:51], -1
	s_waitcnt lgkmcnt(0)
	v_add_u32_e32 v2, s100, v0
	v_cmp_lt_i32_e32 vcc, -1, v2
	s_orn2_b64 s[48:49], vcc, exec
	s_branch .LBB0_894

.LBB0_1047:
	s_load_dword s100, s[22:23], 0x0 glc
	s_add_i32 s26, s26, 1
	s_mov_b64 s[46:47], -1
	s_waitcnt lgkmcnt(0)
	v_cmp_ne_u32_e32 vcc, s100, v0
	s_orn2_b64 s[42:43], vcc, exec
	s_branch .LBB0_1044

.LBB0_1064:
	s_load_dword s100, s[12:13], 0x0 glc
	s_add_i32 s26, s26, 1
	s_mov_b64 s[42:43], -1
	s_waitcnt lgkmcnt(0)
	v_cmp_ne_u32_e32 vcc, s100, v0
	s_orn2_b64 s[40:41], vcc, exec
	s_branch .LBB0_1061

.LBB0_1223:
	s_or_b64 exec, exec, s[10:11]
	s_waitcnt vmcnt(0)
	v_readfirstlane_b32 s6, v2
	s_nop 1
	v_add_u32_e32 v0, s6, v0
	v_and_b32_e32 v2, 31, v0
	v_cmp_ne_u32_e32 vcc, 31, v2
	s_and_saveexec_b64 s[6:7], vcc
	s_cbranch_execz .LBB0_1237
	s_load_dword s100, s[4:5], 0x0 glc
	s_movk_i32 s10, 0xffe0
	v_bitop3_b32 v0, v0, s10, v0 bitop3:0xc
	s_waitcnt lgkmcnt(0)
	v_add_u32_e32 v2, s100, v0
	v_cmp_gt_i32_e32 vcc, 0, v2
	s_and_b64 exec, exec, vcc
	s_cbranch_execz .LBB0_1237
	s_add_u32 s8, s8, 0x4200
	s_addc_u32 s9, s9, 0
	s_mov_b32 s24, 1
	s_mov_b64 s[10:11], 0
	s_branch .LBB0_1227

.LBB0_1229:
	s_load_dword s100, s[4:5], 0x0 glc
	s_add_i32 s24, s24, 1
	s_mov_b64 s[16:17], -1
	s_waitcnt lgkmcnt(0)
	v_add_u32_e32 v2, s100, v0
	v_cmp_lt_i32_e32 vcc, -1, v2
	s_orn2_b64 s[14:15], vcc, exec
	s_branch .LBB0_1226

.LBB0_1263:
	s_load_dword s100, s[14:15], 0x0 glc
	s_add_i32 s26, s26, 1
	s_mov_b64 s[40:41], -1
	s_waitcnt lgkmcnt(0)
	v_cmp_ne_u32_e32 vcc, s100, v0
	s_orn2_b64 s[24:25], vcc, exec
	s_branch .LBB0_1260

.LBB0_1280:
	s_load_dword s100, s[8:9], 0x0 glc
	s_add_i32 s26, s26, 1
	s_mov_b64 s[24:25], -1
	s_waitcnt lgkmcnt(0)
	v_cmp_ne_u32_e32 vcc, s100, v0
	s_orn2_b64 s[22:23], vcc, exec
	s_branch .LBB0_1277

.LBB0_1771:
	s_load_dword s100, s[24:25], 0x0 glc
	s_add_i32 s26, s26, 1
	s_mov_b64 s[48:49], -1
	s_waitcnt lgkmcnt(0)
	v_cmp_ne_u32_e32 vcc, s100, v0
	s_orn2_b64 s[46:47], vcc, exec
	s_branch .LBB0_1768

.LBB0_1788:
	s_load_dword s100, s[14:15], 0x0 glc
	s_add_i32 s26, s26, 1
	s_mov_b64 s[46:47], -1
	s_waitcnt lgkmcnt(0)
	v_cmp_ne_u32_e32 vcc, s100, v0
	s_orn2_b64 s[42:43], vcc, exec
	s_branch .LBB0_1785

.LBB0_1829:
	s_or_b64 exec, exec, s[40:41]
	s_waitcnt vmcnt(0)
	v_readfirstlane_b32 s24, v2
	s_nop 1
	v_add_u32_e32 v0, s24, v0
	v_and_b32_e32 v2, 3, v0
	v_cmp_ne_u32_e32 vcc, 3, v2
	s_and_saveexec_b64 s[24:25], vcc
	s_cbranch_execz .LBB0_1843
	s_load_dword s100, s[22:23], 0x0 glc
	v_bitop3_b32 v0, v0, -4, v0 bitop3:0xc
	s_waitcnt lgkmcnt(0)
	v_add_u32_e32 v2, s100, v0
	v_cmp_gt_i32_e32 vcc, 0, v2
	s_and_b64 exec, exec, vcc
	s_cbranch_execz .LBB0_1843
	s_add_u32 s6, s6, 0x4200
	s_addc_u32 s7, s7, 0
	s_mov_b32 s26, 1
	s_mov_b64 s[40:41], 0
	s_branch .LBB0_1833

.LBB0_1835:
	s_load_dword s100, s[22:23], 0x0 glc
	s_add_i32 s26, s26, 1
	s_mov_b64 s[48:49], -1
	s_waitcnt lgkmcnt(0)
	v_add_u32_e32 v2, s100, v0
	v_cmp_lt_i32_e32 vcc, -1, v2
	s_orn2_b64 s[46:47], vcc, exec
	s_branch .LBB0_1832

.LBB0_1911:
	s_or_b64 exec, exec, s[10:11]
	s_waitcnt vmcnt(0)
	v_readfirstlane_b32 s6, v2
	s_nop 1
	v_add_u32_e32 v0, s6, v0
	v_and_b32_e32 v2, 3, v0
	v_cmp_ne_u32_e32 vcc, 3, v2
	s_and_saveexec_b64 s[6:7], vcc
	s_cbranch_execz .LBB0_1925
	s_load_dword s100, s[4:5], 0x0 glc
	v_bitop3_b32 v0, v0, -4, v0 bitop3:0xc
	s_waitcnt lgkmcnt(0)
	v_add_u32_e32 v2, s100, v0
	v_cmp_gt_i32_e32 vcc, 0, v2
	s_and_b64 exec, exec, vcc
	s_cbranch_execz .LBB0_1925
	s_add_u32 s8, s8, 0x4200
	s_addc_u32 s9, s9, 0
	s_mov_b32 s24, 1
	s_mov_b64 s[10:11], 0
	s_branch .LBB0_1915

.LBB0_2028:
	s_load_dword s100, s[14:15], 0x0 glc
	s_add_i32 s26, s26, 1
	s_mov_b64 s[28:29], -1
	s_waitcnt lgkmcnt(0)
	v_cmp_ne_u32_e32 vcc, s100, v0
	s_orn2_b64 s[24:25], vcc, exec
	s_branch .LBB0_2025
